# P1: L2 touch-prefetch of next trip's two x rows
# baseline (speedup 1.0000x reference)
.LBB0_165:
	s_or_b64 exec, exec, s[0:1]
	v_mov_b32_e32 v3, v0
	s_waitcnt lgkmcnt(0)
	s_barrier
	s_lshl_b32 s26, s2, 2
	v_ashrrev_i32_e32 v2, 6, v3
	v_add_u32_e32 v35, s26, v2
	s_movk_i32 s0, 0x3000
	s_lshl_b32 s28, s99, 2
	v_cmp_gt_i32_e32 vcc, s0, v35
	v_mbcnt_lo_u32_b32 v1, -1, 0
	s_and_saveexec_b64 s[0:1], vcc
	s_cbranch_execz .LBB0_174
	v_and_b32_e32 v4, 63, v3
	v_mbcnt_hi_u32_b32 v3, -1, v1
	v_lshlrev_b32_e32 v204, 6, v3
	v_mov_b32_e32 v205, 0
	v_and_b32_e32 v5, 64, v3
	v_add_u32_e32 v5, 64, v5
	v_xor_b32_e32 v6, 32, v3
	v_cmp_lt_i32_e32 vcc, v6, v5
	s_ashr_i32 s27, s26, 31
	v_lshlrev_b32_e32 v18, 3, v4
	v_cndmask_b32_e32 v6, v3, v6, vcc
	v_lshlrev_b32_e32 v42, 2, v6
	v_xor_b32_e32 v6, 16, v3
	v_cmp_lt_i32_e32 vcc, v6, v5
	v_mov_b32_e32 v19, 0
	s_ashr_i32 s29, s28, 31
	v_cndmask_b32_e32 v6, v3, v6, vcc
	v_lshlrev_b32_e32 v43, 2, v6
	v_xor_b32_e32 v6, 8, v3
	v_cmp_lt_i32_e32 vcc, v6, v5
	v_lshl_add_u64 v[20:21], s[48:49], 0, v[18:19]
	s_lshl_b64 s[4:5], s[28:29], 12
	v_cndmask_b32_e32 v6, v3, v6, vcc
	v_lshlrev_b32_e32 v44, 2, v6
	v_xor_b32_e32 v6, 4, v3
	v_cmp_lt_i32_e32 vcc, v6, v5
	s_lshl_b64 s[6:7], s[28:29], 11
	s_mov_b64 s[8:9], 0
	v_cndmask_b32_e32 v6, v3, v6, vcc
	v_lshlrev_b32_e32 v45, 2, v6
	v_xor_b32_e32 v6, 2, v3
	v_cmp_lt_i32_e32 vcc, v6, v5
	s_movk_i32 s3, 0x1fff
	s_movk_i32 s13, 0xc00
	v_cndmask_b32_e32 v6, v3, v6, vcc
	v_lshlrev_b32_e32 v46, 2, v6
	v_xor_b32_e32 v6, 1, v3
	v_cmp_lt_i32_e32 vcc, v6, v5
	s_movk_i32 s16, 0xefff
	s_mov_b64 s[10:11], 0x1000
	v_cndmask_b32_e32 v3, v3, v6, vcc
	v_lshlrev_b32_e32 v47, 2, v3
	v_ashrrev_i32_e32 v3, 31, v2
	v_lshl_add_u64 v[2:3], v[2:3], 0, s[26:27]
	v_lshlrev_b32_e32 v6, 2, v4
	v_lshlrev_b64 v[14:15], 12, v[2:3]
	v_lshlrev_b64 v[2:3], 11, v[2:3]
	v_or_b32_e32 v8, 0x100, v6
	v_or_b32_e32 v10, 0x200, v6
	v_or_b32_e32 v12, 0x300, v6
	v_or_b32_e32 v2, v2, v18
	v_lshl_add_u64 v[22:23], s[56:57], 0, v[14:15]
	v_lshl_add_u64 v[24:25], s[48:49], 0, v[2:3]
	v_lshlrev_b32_e32 v18, 4, v4
	v_lshlrev_b32_e32 v26, 2, v6
	v_lshlrev_b32_e32 v28, 2, v8
	v_lshlrev_b32_e32 v30, 2, v10
	v_lshlrev_b32_e32 v32, 2, v12
	s_mov_b32 s12, 0x3a800000
	s_mov_b32 s17, 0x800000
	s_movk_i32 s18, 0x2fff
	v_mov_b32_e32 v34, 0x358637bd
	s_branch .LBB0_168
.LBB0_167:
	s_or_b64 exec, exec, s[14:15]
	v_lshl_add_u64 v[4:5], v[4:5], 0, v[18:19]
	global_load_dwordx4 v[48:51], v[4:5], off
	global_load_dwordx4 v[52:55], v[4:5], off offset:1024
	global_load_dwordx4 v[56:59], v[4:5], off offset:2048
	global_load_dwordx4 v[60:63], v[4:5], off offset:3072
	v_lshl_add_u64 v[2:3], v[2:3], 0, v[18:19]
	global_load_dwordx4 v[14:17], v[2:3], off
	global_load_dwordx4 v[10:13], v[2:3], off offset:1024
	global_load_dwordx4 v[6:9], v[2:3], off offset:2048
	s_nop 0
	global_load_dwordx4 v[2:5], v[2:3], off offset:3072
	v_lshl_add_u64 v[40:41], v[40:41], 2, s[40:41]
	v_mov_b32_e32 v27, v19
	v_lshl_add_u64 v[72:73], v[40:41], 0, s[10:11]
	v_lshl_add_u64 v[40:41], v[40:41], 0, v[26:27]
	v_lshl_add_u64 v[68:69], v[72:73], 0, v[26:27]
	global_load_dwordx4 v[64:67], v[40:41], off
	s_nop 0
	global_load_dwordx4 v[68:71], v[68:69], off
	v_lshl_add_u64 v[142:143], v[72:73], 0, v[26:27]
	global_load_dwordx4 v[144:147], v[40:41], off offset:1024
	global_load_dwordx4 v[148:151], v[40:41], off offset:2048
	global_load_dwordx4 v[152:155], v[40:41], off offset:3072
	global_load_dwordx4 v[156:159], v[142:143], off offset:1024
	global_load_dwordx4 v[160:163], v[142:143], off offset:2048
	global_load_dwordx4 v[164:167], v[142:143], off offset:3072
	v_lshl_add_u64 v[168:169], v[38:39], 2, s[40:41]
	v_lshl_add_u64 v[168:169], v[168:169], 0, v[26:27]
	v_lshl_add_u64 v[170:171], v[168:169], 0, s[10:11]
	global_load_dwordx4 v[172:175], v[168:169], off
	global_load_dwordx4 v[176:179], v[168:169], off offset:1024
	global_load_dwordx4 v[180:183], v[168:169], off offset:2048
	global_load_dwordx4 v[184:187], v[168:169], off offset:3072
	global_load_dwordx4 v[188:191], v[170:171], off
	global_load_dwordx4 v[192:195], v[170:171], off offset:1024
	global_load_dwordx4 v[196:199], v[170:171], off offset:2048
	global_load_dwordx4 v[200:203], v[170:171], off offset:3072
	v_add_u32_e32 v206, s28, v35
	v_cmp_gt_i32_e32 vcc, 0x3000, v206
	s_nop 1
	v_cndmask_b32_e32 v206, v35, v206, vcc
	v_add_u32_e32 v222, 0x1000, v206
	v_mov_b32_e32 v223, 0
	v_lshlrev_b64 v[222:223], 12, v[222:223]
	v_lshl_add_u64 v[222:223], s[58:59], 0, v[222:223]
	v_lshl_add_u64 v[222:223], v[222:223], 0, v[204:205]
	global_load_dword v220, v[222:223], off
	v_cmp_gt_i32_e32 vcc, 0x2000, v206
	v_subrev_u32_e32 v224, 0x2000, v206
	v_mov_b32_e32 v226, s58
	v_mov_b32_e32 v227, s59
	v_mov_b32_e32 v228, s56
	v_mov_b32_e32 v229, s57
	v_cndmask_b32_e32 v224, v224, v206, vcc
	v_cndmask_b32_e32 v226, v226, v228, vcc
	v_cndmask_b32_e32 v227, v227, v229, vcc
	v_mov_b32_e32 v225, 0
	v_lshlrev_b64 v[224:225], 12, v[224:225]
	v_lshl_add_u64 v[224:225], v[224:225], 0, v[226:227]
	v_lshl_add_u64 v[224:225], v[224:225], 0, v[204:205]
	global_load_dword v221, v[224:225], off
	v_mov_b32_e32 v29, v19
	v_lshlrev_b64 v[36:37], 11, v[36:37]
	v_lshl_add_u64 v[22:23], v[22:23], 0, s[4:5]
	s_waitcnt vmcnt(25)
	v_mov_b32_e32 v80, v49
	s_waitcnt vmcnt(24)
	v_mov_b32_e32 v81, v53
	s_waitcnt vmcnt(23)
	v_mov_b32_e32 v88, v57
	s_waitcnt vmcnt(22)
	v_mov_b32_e32 v89, v61
	s_waitcnt vmcnt(21)
	v_mov_b32_e32 v96, v15
	s_waitcnt vmcnt(20)
	v_mov_b32_e32 v97, v11
	v_mov_b32_e32 v78, v48
	v_mov_b32_e32 v79, v52
	v_mov_b32_e32 v86, v56
	v_mov_b32_e32 v87, v60
	v_mov_b32_e32 v94, v14
	v_mov_b32_e32 v95, v10
	s_waitcnt vmcnt(19)
	v_mov_b32_e32 v104, v7
	s_waitcnt vmcnt(18)
	v_mov_b32_e32 v105, v3
	v_pk_mul_f32 v[80:81], v[80:81], v[80:81]
	v_pk_mul_f32 v[88:89], v[88:89], v[88:89]
	v_pk_mul_f32 v[96:97], v[96:97], v[96:97]
	v_mov_b32_e32 v74, v50
	v_mov_b32_e32 v75, v54
	v_mov_b32_e32 v82, v58
	v_mov_b32_e32 v83, v62
	v_mov_b32_e32 v90, v16
	v_mov_b32_e32 v91, v12
	v_mov_b32_e32 v102, v6
	v_mov_b32_e32 v103, v2
	v_pk_mul_f32 v[104:105], v[104:105], v[104:105]
	v_pk_fma_f32 v[78:79], v[78:79], v[78:79], v[80:81]
	v_pk_fma_f32 v[80:81], v[86:87], v[86:87], v[88:89]
	v_pk_fma_f32 v[86:87], v[94:95], v[94:95], v[96:97]
	v_mov_b32_e32 v76, v51
	v_mov_b32_e32 v77, v55
	v_mov_b32_e32 v84, v59
	v_mov_b32_e32 v85, v63
	v_mov_b32_e32 v92, v17
	v_mov_b32_e32 v93, v13
	v_mov_b32_e32 v98, v8
	v_mov_b32_e32 v99, v4
	v_pk_fma_f32 v[88:89], v[102:103], v[102:103], v[104:105]
	v_pk_fma_f32 v[74:75], v[74:75], v[74:75], v[78:79]
	v_pk_fma_f32 v[78:79], v[82:83], v[82:83], v[80:81]
	v_pk_fma_f32 v[80:81], v[90:91], v[90:91], v[86:87]
	v_mov_b32_e32 v100, v9
	v_mov_b32_e32 v101, v5
	v_pk_fma_f32 v[82:83], v[98:99], v[98:99], v[88:89]
	v_pk_fma_f32 v[74:75], v[76:77], v[76:77], v[74:75]
	v_pk_fma_f32 v[76:77], v[84:85], v[84:85], v[78:79]
	v_pk_fma_f32 v[78:79], v[92:93], v[92:93], v[80:81]
	v_pk_fma_f32 v[80:81], v[100:101], v[100:101], v[82:83]
	v_mov_b32_e32 v82, v78
	v_mov_b32_e32 v83, v74
	v_mov_b32_e32 v74, v79
	v_mov_b32_e32 v78, v80
	v_mov_b32_e32 v79, v76
	v_pk_add_f32 v[74:75], v[82:83], v[74:75]
	v_mov_b32_e32 v76, v81
	v_pk_add_f32 v[74:75], v[74:75], v[78:79]
	s_waitcnt vmcnt(2)
	v_pk_add_f32 v[68:69], v[68:69], 1.0 op_sel_hi:[1,0]
	v_pk_add_f32 v[74:75], v[74:75], v[76:77]
	ds_bpermute_b32 v77, v42, v75
	ds_bpermute_b32 v76, v42, v74
	v_pk_add_f32 v[70:71], v[70:71], 1.0 op_sel_hi:[1,0]
	s_waitcnt lgkmcnt(0)
	v_pk_add_f32 v[74:75], v[74:75], v[76:77]
	ds_bpermute_b32 v77, v43, v75
	ds_bpermute_b32 v76, v43, v74
	s_waitcnt lgkmcnt(0)
	v_pk_add_f32 v[74:75], v[74:75], v[76:77]
	ds_bpermute_b32 v77, v44, v75
	ds_bpermute_b32 v76, v44, v74
	s_waitcnt lgkmcnt(0)
	v_pk_add_f32 v[74:75], v[74:75], v[76:77]
	ds_bpermute_b32 v77, v45, v75
	ds_bpermute_b32 v76, v45, v74
	s_waitcnt lgkmcnt(0)
	v_pk_add_f32 v[74:75], v[74:75], v[76:77]
	ds_bpermute_b32 v77, v46, v75
	ds_bpermute_b32 v76, v46, v74
	s_waitcnt lgkmcnt(0)
	v_pk_add_f32 v[74:75], v[74:75], v[76:77]
	ds_bpermute_b32 v77, v47, v75
	ds_bpermute_b32 v76, v47, v74
	s_waitcnt lgkmcnt(0)
	v_pk_add_f32 v[74:75], v[74:75], v[76:77]
	s_nop 0
	v_pk_fma_f32 v[74:75], v[74:75], s[12:13], v[34:35] op_sel_hi:[1,0,0]
	v_lshl_add_u64 v[76:77], v[72:73], 0, v[28:29]
	v_mul_f32_e32 v31, 0x4b800000, v75
	v_cmp_gt_f32_e32 vcc, s17, v75
	v_add_u32_e32 v35, s28, v35
	s_nop 0
	v_cndmask_b32_e32 v31, v75, v31, vcc
	v_rsq_f32_e32 v31, v31
	s_nop 0
	v_mul_f32_e32 v33, 0x45800000, v31
	v_cndmask_b32_e32 v78, v31, v33, vcc
	v_pk_mul_f32 v[48:49], v[48:49], v[78:79] op_sel_hi:[1,0]
	v_pk_mul_f32 v[50:51], v[50:51], v[78:79] op_sel_hi:[1,0]
	v_pk_fma_f32 v[48:49], v[68:69], v[48:49], v[64:65]
	v_pk_fma_f32 v[50:51], v[70:71], v[50:51], v[66:67]
	v_cvt_pk_bf16_f32 v48, v48, v49
	v_cvt_pk_bf16_f32 v49, v50, v51
	global_store_dwordx2 v[24:25], v[48:49], off
	v_cmp_gt_f32_e32 vcc, s17, v74
	v_pk_mul_f32 v[52:53], v[52:53], v[78:79] op_sel_hi:[1,0]
	v_pk_mul_f32 v[54:55], v[54:55], v[78:79] op_sel_hi:[1,0]
	v_pk_mul_f32 v[56:57], v[56:57], v[78:79] op_sel_hi:[1,0]
	v_pk_mul_f32 v[58:59], v[58:59], v[78:79] op_sel_hi:[1,0]
	v_pk_mul_f32 v[60:61], v[60:61], v[78:79] op_sel_hi:[1,0]
	v_pk_mul_f32 v[62:63], v[62:63], v[78:79] op_sel_hi:[1,0]
	v_pk_add_f32 v[156:157], v[156:157], 1.0 op_sel_hi:[1,0]
	v_pk_add_f32 v[158:159], v[158:159], 1.0 op_sel_hi:[1,0]
	v_pk_fma_f32 v[52:53], v[52:53], v[156:157], v[144:145]
	v_pk_fma_f32 v[54:55], v[54:55], v[158:159], v[146:147]
	v_cvt_pk_bf16_f32 v52, v52, v53
	v_cvt_pk_bf16_f32 v53, v54, v55
	global_store_dwordx2 v[24:25], v[52:53], off offset:512
	v_pk_add_f32 v[160:161], v[160:161], 1.0 op_sel_hi:[1,0]
	v_pk_add_f32 v[162:163], v[162:163], 1.0 op_sel_hi:[1,0]
	v_pk_fma_f32 v[56:57], v[56:57], v[160:161], v[148:149]
	v_pk_fma_f32 v[58:59], v[58:59], v[162:163], v[150:151]
	v_cvt_pk_bf16_f32 v56, v56, v57
	v_cvt_pk_bf16_f32 v57, v58, v59
	global_store_dwordx2 v[24:25], v[56:57], off offset:1024
	v_pk_add_f32 v[164:165], v[164:165], 1.0 op_sel_hi:[1,0]
	v_pk_add_f32 v[166:167], v[166:167], 1.0 op_sel_hi:[1,0]
	v_pk_fma_f32 v[60:61], v[60:61], v[164:165], v[152:153]
	v_pk_fma_f32 v[62:63], v[62:63], v[166:167], v[154:155]
	v_cvt_pk_bf16_f32 v60, v60, v61
	v_cvt_pk_bf16_f32 v61, v62, v63
	global_store_dwordx2 v[24:25], v[60:61], off offset:1536
	v_mul_f32_e32 v27, 0x4b800000, v74
	v_cndmask_b32_e32 v27, v74, v27, vcc
	v_rsq_f32_e32 v27, v27
	v_lshl_add_u64 v[54:55], v[20:21], 0, v[36:37]
	v_lshl_add_u64 v[24:25], v[24:25], 0, s[6:7]
	v_mul_f32_e32 v29, 0x45800000, v27
	v_cndmask_b32_e32 v56, v27, v29, vcc
	v_pk_mul_f32 v[14:15], v[14:15], v[56:57] op_sel_hi:[1,0]
	v_pk_mul_f32 v[16:17], v[16:17], v[56:57] op_sel_hi:[1,0]
	v_pk_mul_f32 v[10:11], v[10:11], v[56:57] op_sel_hi:[1,0]
	v_pk_mul_f32 v[12:13], v[12:13], v[56:57] op_sel_hi:[1,0]
	v_pk_mul_f32 v[6:7], v[6:7], v[56:57] op_sel_hi:[1,0]
	v_pk_mul_f32 v[8:9], v[8:9], v[56:57] op_sel_hi:[1,0]
	v_pk_mul_f32 v[2:3], v[2:3], v[56:57] op_sel_hi:[1,0]
	v_pk_mul_f32 v[4:5], v[4:5], v[56:57] op_sel_hi:[1,0]
	v_cmp_lt_i32_e32 vcc, s18, v35
	s_or_b64 s[8:9], vcc, s[8:9]
	v_pk_add_f32 v[188:189], v[188:189], 1.0 op_sel_hi:[1,0]
	v_pk_add_f32 v[190:191], v[190:191], 1.0 op_sel_hi:[1,0]
	v_pk_fma_f32 v[14:15], v[14:15], v[188:189], v[172:173]
	v_pk_fma_f32 v[16:17], v[16:17], v[190:191], v[174:175]
	v_cvt_pk_bf16_f32 v14, v14, v15
	v_cvt_pk_bf16_f32 v15, v16, v17
	global_store_dwordx2 v[54:55], v[14:15], off
	v_pk_add_f32 v[192:193], v[192:193], 1.0 op_sel_hi:[1,0]
	v_pk_add_f32 v[194:195], v[194:195], 1.0 op_sel_hi:[1,0]
	v_pk_fma_f32 v[10:11], v[10:11], v[192:193], v[176:177]
	v_pk_fma_f32 v[12:13], v[12:13], v[194:195], v[178:179]
	v_cvt_pk_bf16_f32 v10, v10, v11
	v_cvt_pk_bf16_f32 v11, v12, v13
	global_store_dwordx2 v[54:55], v[10:11], off offset:512
	v_pk_add_f32 v[196:197], v[196:197], 1.0 op_sel_hi:[1,0]
	v_pk_add_f32 v[198:199], v[198:199], 1.0 op_sel_hi:[1,0]
	v_pk_fma_f32 v[6:7], v[6:7], v[196:197], v[180:181]
	v_pk_fma_f32 v[8:9], v[8:9], v[198:199], v[182:183]
	v_cvt_pk_bf16_f32 v6, v6, v7
	v_cvt_pk_bf16_f32 v7, v8, v9
	global_store_dwordx2 v[54:55], v[6:7], off offset:1024
	v_pk_add_f32 v[200:201], v[200:201], 1.0 op_sel_hi:[1,0]
	v_pk_add_f32 v[202:203], v[202:203], 1.0 op_sel_hi:[1,0]
	v_pk_fma_f32 v[2:3], v[2:3], v[200:201], v[184:185]
	v_pk_fma_f32 v[4:5], v[4:5], v[202:203], v[186:187]
	v_cvt_pk_bf16_f32 v2, v2, v3
	v_cvt_pk_bf16_f32 v3, v4, v5
	global_store_dwordx2 v[54:55], v[2:3], off offset:1536
	s_andn2_b64 exec, exec, s[8:9]
	s_cbranch_execz .LBB0_174
